# conv loads software-pipelined one token ahead (fixed: no fetch-ahead on the item's last token), on top of prep_item prefetch
# speedup vs baseline: 1.0130x; 1.0087x over previous
; __device__ __forceinline__ unsigned pk_bf16(float a, float b) { f32x2 v = {a, b}; bf2_t r = __builtin_convertvector(v, bf2_t); return __builtin_bit_cast(unsigned, r); }
; __device__ __forceinline__ float bf_lo(unsigned u) { return __uint_as_float(u << 16); }
; __device__ __forceinline__ float bf_hi(unsigned u) { return __uint_as_float(u & 0xffff0000u); }
; __device__ void phase_conv(const Params& p, int l, int nrows) {
;     ...
;         for (int i = 0; i < 16; ++i) {
;             const bf16_t* np = gp + (size_t)(i + 1) * FF;
;             const bool v = (c0 + i + 1) < W;
;             R[0] = (v && up) ? *(const u32x4*)(np - (size_t)64 * FF) : zero; R[1] = v ? *(const u32x4*)np : zero; R[2] = (v && dn) ? *(const u32x4*)(np + (size_t)64 * FF) : zero;
;             float acc[8];
; #pragma unroll
;             for (int j = 0; j < 8; ++j) acc[j] = bias[j];
; #pragma unroll
;             for (int rr = 0; rr < 3; ++rr) {
; #pragma unroll
;                 for (int j = 0; j < 4; ++j) {
;                     acc[2 * j] += bf_lo(L[rr][j]) * tp[rr * 3 + 0][2 * j] + bf_lo(M[rr][j]) * tp[rr * 3 + 1][2 * j] + bf_lo(R[rr][j]) * tp[rr * 3 + 2][2 * j];
;                     acc[2 * j + 1] += bf_hi(L[rr][j]) * tp[rr * 3 + 0][2 * j + 1] + bf_hi(M[rr][j]) * tp[rr * 3 + 1][2 * j + 1] + bf_hi(R[rr][j]) * tp[rr * 3 + 2][2 * j + 1];
;                 }
;             }
;             bf16_t* ap = Aup + (size_t)(tok0 + i) * FF + f0;
;             const u32x4 av = __builtin_nontemporal_load((const u32x4*)ap);
;             u32x4 wv;
; #pragma unroll
;             for (int j = 0; j < 4; ++j) wv[j] = pk_bf16(bf_lo(av[j]) * gelu_f(acc[2 * j]), bf_hi(av[j]) * gelu_f(acc[2 * j + 1]));
;             *(u32x4*)ap = wv;
; #pragma unroll
;             for (int rr = 0; rr < 3; ++rr) { L[rr] = M[rr]; M[rr] = R[rr]; }
.LBB0_718:
	s_or_b64 exec, exec, s[66:67]
	v_add_co_u32_e32 v10, vcc, 0x7fb6000, v124
	v_pk_mul_f32 v[140:141], v[32:33], v[140:141]
	s_nop 0
	v_addc_co_u32_e32 v11, vcc, 0, v125, vcc
	v_pk_mul_f32 v[124:125], v[12:13], v[174:175]
	v_pk_fma_f32 v[140:141], v[40:41], v[150:151], v[140:141]
	v_pk_fma_f32 v[124:125], v[4:5], v[148:149], v[124:125]
	s_waitcnt vmcnt(1)
	v_mov_b64_e32 v[104:105], v[200:201]
	v_mov_b64_e32 v[106:107], v[202:203]
	v_mov_b64_e32 v[100:101], v[204:205]
	v_mov_b64_e32 v[102:103], v[206:207]
	v_mov_b64_e32 v[96:97], v[208:209]
	v_mov_b64_e32 v[98:99], v[210:211]
	v_mov_b64_e32 v[108:109], v[196:197]
	v_mov_b64_e32 v[110:111], v[198:199]
	s_cmp_lg_u32 s88, 0
	s_cbranch_scc1 .Lconv_nopf
	v_add_u32_e32 v214, 1, v188
	v_cmp_lt_u32_e64 s[98:99], v214, v187
	s_add_u32 s100, s20, 0x7fb8000
	s_addc_u32 s101, s21, 0
	global_load_dwordx4 v[196:199], v192, s[100:101] nt
	v_mov_b32_e32 v200, 0
	v_mov_b32_e32 v201, 0
	v_mov_b32_e32 v202, 0
	v_mov_b32_e32 v203, 0
	v_mov_b32_e32 v204, 0
	v_mov_b32_e32 v205, 0
	v_mov_b32_e32 v206, 0
	v_mov_b32_e32 v207, 0
	v_mov_b32_e32 v208, 0
	v_mov_b32_e32 v209, 0
	v_mov_b32_e32 v210, 0
	v_mov_b32_e32 v211, 0
	s_add_u32 s10, s20, 0x13ab9600
	s_addc_u32 s11, s21, 0
	s_and_saveexec_b64 s[22:23], s[98:99]
	global_load_dwordx4 v[204:207], v192, s[10:11]
	s_add_u32 s100, s20, 0x13a61600
	s_addc_u32 s101, s21, 0
	s_and_b64 exec, exec, s[40:41]
	global_load_dwordx4 v[200:203], v192, s[100:101]
	s_add_u32 s10, s20, 0x13b11600
	s_addc_u32 s11, s21, 0
	s_and_b64 exec, s[22:23], s[98:99]
	s_and_b64 exec, exec, s[42:43]
	global_load_dwordx4 v[208:211], v192, s[10:11]
	s_mov_b64 exec, s[22:23]
.Lconv_nopf:
	v_lshlrev_b32_e32 v148, 16, v104
	v_and_b32_e32 v149, 0xffff0000, v104
	v_pk_fma_f32 v[124:125], v[20:21], v[148:149], v[124:125]
	v_pk_mul_f32 v[148:149], v[28:29], v[164:165]
	v_lshlrev_b32_e32 v164, 16, v100
	v_pk_fma_f32 v[148:149], v[36:37], v[170:171], v[148:149]
	v_and_b32_e32 v165, 0xffff0000, v100
	v_pk_add_f32 v[124:125], v[80:81], v[124:125]
	v_pk_fma_f32 v[148:149], v[44:45], v[164:165], v[148:149]
	v_pk_mul_f32 v[126:127], v[56:57], v[126:127]
	v_pk_add_f32 v[124:125], v[124:125], v[148:149]
	v_pk_mul_f32 v[148:149], v[52:53], v[162:163]
	v_lshlrev_b32_e32 v162, 16, v96
	v_pk_fma_f32 v[148:149], v[60:61], v[168:169], v[148:149]
	v_and_b32_e32 v163, 0xffff0000, v96
	v_pk_fma_f32 v[148:149], v[68:69], v[162:163], v[148:149]
	v_pk_fma_f32 v[126:127], v[64:65], v[144:145], v[126:127]
	v_pk_add_f32 v[148:149], v[124:125], v[148:149]
	v_mov_b64_e32 v[124:125], s[90:91]
	v_fma_f32 v9, |v148|, s80, 1.0
	v_pk_mul_f32 v[164:165], v[148:149], v[148:149]
	v_rcp_f32_e32 v162, v9
	v_mul_f32_e32 v9, 0xbf38aa3b, v164
	v_exp_f32_e32 v164, v9
	v_fma_f32 v9, |v149|, s80, 1.0
	v_rcp_f32_e32 v163, v9
	v_mul_f32_e32 v9, 0xbf38aa3b, v165
	v_exp_f32_e32 v165, v9
	v_cmp_gt_f32_e32 vcc, 0, v148
	v_pk_fma_f32 v[170:171], v[162:163], s[68:69], v[124:125] op_sel_hi:[1,0,0]
	v_cmp_gt_f32_e64 s[0:1], 0, v149
	v_pk_fma_f32 v[170:171], v[162:163], v[170:171], s[44:45] op_sel_hi:[1,1,0]
	v_pk_mul_f32 v[116:117], v[34:35], v[116:117]
	v_pk_fma_f32 v[170:171], v[162:163], v[170:171], s[84:85] op_sel_hi:[1,1,0]
	v_pk_fma_f32 v[116:117], v[42:43], v[142:143], v[116:117]
	v_pk_fma_f32 v[170:171], v[162:163], v[170:171], s[64:65] op_sel_hi:[1,1,0]
	v_pk_mul_f32 v[114:115], v[58:59], v[114:115]
	v_pk_mul_f32 v[162:163], v[162:163], v[170:171]
	v_pk_fma_f32 v[112:113], v[66:67], v[112:113], v[114:115]
	v_pk_mul_f32 v[162:163], v[164:165], v[162:163]
	v_lshlrev_b32_e32 v114, 16, v99
	v_pk_mul_f32 v[164:165], v[148:149], v[162:163]
	v_pk_fma_f32 v[148:149], v[148:149], v[162:163], v[148:149] neg_lo:[1,0,0] neg_hi:[1,0,0]
	v_and_b32_e32 v115, 0xffff0000, v99
	v_cndmask_b32_e64 v149, v149, v165, s[0:1]
	v_cndmask_b32_e32 v148, v148, v164, vcc
	v_pk_fma_f32 v[112:113], v[74:75], v[114:115], v[112:113]
	s_add_u32 s88, s88, 0xb000
	s_addc_u32 s89, s89, 0
	v_add_u32_e32 v188, 8, v188
	s_cmp_eq_u32 s88, 0x16000
	s_nop 0
	v_lshlrev_b32_e32 v168, 16, v108
	v_and_b32_e32 v169, 0xffff0000, v108
	v_pk_mul_f32 v[148:149], v[148:149], v[168:169]
	v_lshlrev_b32_e32 v144, 16, v110
	v_cvt_pk_bf16_f32 v108, v148, v149
	v_pk_mul_f32 v[148:149], v[14:15], v[172:173]
	v_and_b32_e32 v145, 0xffff0000, v110
	v_pk_fma_f32 v[146:147], v[6:7], v[146:147], v[148:149]
	v_lshlrev_b32_e32 v148, 16, v105
	v_and_b32_e32 v149, 0xffff0000, v105
	v_pk_fma_f32 v[146:147], v[22:23], v[148:149], v[146:147]
	v_pk_mul_f32 v[148:149], v[30:31], v[160:161]
	v_lshlrev_b32_e32 v160, 16, v101
	v_pk_fma_f32 v[148:149], v[38:39], v[166:167], v[148:149]
	v_and_b32_e32 v161, 0xffff0000, v101
	v_pk_add_f32 v[146:147], v[82:83], v[146:147]
	v_pk_fma_f32 v[148:149], v[46:47], v[160:161], v[148:149]
	s_nop 0
	v_pk_add_f32 v[146:147], v[146:147], v[148:149]
	v_pk_mul_f32 v[148:149], v[54:55], v[158:159]
	v_lshlrev_b32_e32 v158, 16, v109
	v_pk_fma_f32 v[148:149], v[62:63], v[156:157], v[148:149]
; __device__ __forceinline__ unsigned pk_bf16(float a, float b) { f32x2 v = {a, b}; bf2_t r = __builtin_convertvector(v, bf2_t); return __builtin_bit_cast(unsigned, r); }
; __device__ __forceinline__ float bf_lo(unsigned u) { return __uint_as_float(u << 16); }
; __device__ __forceinline__ float bf_hi(unsigned u) { return __uint_as_float(u & 0xffff0000u); }
; __device__ void phase_conv(const Params& p, int l, int nrows) {
;     ...
;             bf16_t* ap = Aup + (size_t)(tok0 + i) * FF + f0;
;             const u32x4 av = __builtin_nontemporal_load((const u32x4*)ap);
;             u32x4 wv;
; #pragma unroll
;             for (int j = 0; j < 4; ++j) wv[j] = pk_bf16(bf_lo(av[j]) * gelu_f(acc[2 * j]), bf_hi(av[j]) * gelu_f(acc[2 * j + 1]));
;             *(u32x4*)ap = wv;
; #pragma unroll
;             for (int rr = 0; rr < 3; ++rr) { L[rr] = M[rr]; M[rr] = R[rr]; }
	v_lshlrev_b32_e32 v156, 16, v97
	v_and_b32_e32 v157, 0xffff0000, v97
	v_pk_fma_f32 v[148:149], v[70:71], v[156:157], v[148:149]
	v_and_b32_e32 v159, 0xffff0000, v109
	v_pk_add_f32 v[146:147], v[146:147], v[148:149]
	s_nop 0
	v_fma_f32 v9, |v146|, s80, 1.0
	v_pk_mul_f32 v[156:157], v[146:147], v[146:147]
	v_rcp_f32_e32 v148, v9
	v_mul_f32_e32 v9, 0xbf38aa3b, v156
	v_exp_f32_e32 v156, v9
	v_fma_f32 v9, |v147|, s80, 1.0
	v_rcp_f32_e32 v149, v9
	v_mul_f32_e32 v9, 0xbf38aa3b, v157
	v_exp_f32_e32 v157, v9
	v_cmp_gt_f32_e32 vcc, 0, v146
	v_pk_fma_f32 v[160:161], v[148:149], s[68:69], v[124:125] op_sel_hi:[1,0,0]
	v_cmp_gt_f32_e64 s[0:1], 0, v147
	v_pk_fma_f32 v[160:161], v[148:149], v[160:161], s[44:45] op_sel_hi:[1,1,0]
	s_nop 0
	v_pk_fma_f32 v[160:161], v[148:149], v[160:161], s[84:85] op_sel_hi:[1,1,0]
	s_nop 0
	v_pk_fma_f32 v[160:161], v[148:149], v[160:161], s[64:65] op_sel_hi:[1,1,0]
	s_nop 0
	v_pk_mul_f32 v[148:149], v[148:149], v[160:161]
	s_nop 0
	v_pk_mul_f32 v[148:149], v[156:157], v[148:149]
	s_nop 0
	v_pk_mul_f32 v[156:157], v[146:147], v[148:149]
	v_pk_fma_f32 v[146:147], v[146:147], v[148:149], v[146:147] neg_lo:[1,0,0] neg_hi:[1,0,0]
	s_nop 0
	v_cndmask_b32_e64 v147, v147, v157, s[0:1]
	v_cndmask_b32_e32 v146, v146, v156, vcc
	v_pk_mul_f32 v[146:147], v[146:147], v[158:159]
	s_nop 0
	v_cvt_pk_bf16_f32 v109, v146, v147
	v_pk_mul_f32 v[146:147], v[16:17], v[154:155]
	s_nop 0
	v_pk_fma_f32 v[128:129], v[0:1], v[128:129], v[146:147]
	v_lshlrev_b32_e32 v146, 16, v106
	v_and_b32_e32 v147, 0xffff0000, v106
	v_pk_fma_f32 v[128:129], v[24:25], v[146:147], v[128:129]
	v_lshlrev_b32_e32 v146, 16, v102
	v_and_b32_e32 v147, 0xffff0000, v102
	v_pk_add_f32 v[128:129], v[76:77], v[128:129]
	v_pk_fma_f32 v[140:141], v[48:49], v[146:147], v[140:141]
	s_nop 0
	v_pk_add_f32 v[128:129], v[128:129], v[140:141]
	v_lshlrev_b32_e32 v140, 16, v98
	v_and_b32_e32 v141, 0xffff0000, v98
	v_pk_fma_f32 v[126:127], v[72:73], v[140:141], v[126:127]
	s_nop 0
	v_pk_add_f32 v[126:127], v[128:129], v[126:127]
	s_nop 0
	v_fma_f32 v9, |v126|, s80, 1.0
	v_pk_mul_f32 v[140:141], v[126:127], v[126:127]
	v_rcp_f32_e32 v128, v9
	v_mul_f32_e32 v9, 0xbf38aa3b, v140
	v_exp_f32_e32 v140, v9
	v_fma_f32 v9, |v127|, s80, 1.0
	v_rcp_f32_e32 v129, v9
	v_mul_f32_e32 v9, 0xbf38aa3b, v141
	v_exp_f32_e32 v141, v9
	v_cmp_gt_f32_e32 vcc, 0, v126
	v_pk_fma_f32 v[146:147], v[128:129], s[68:69], v[124:125] op_sel_hi:[1,0,0]
	v_cmp_gt_f32_e64 s[0:1], 0, v127
	v_pk_fma_f32 v[146:147], v[128:129], v[146:147], s[44:45] op_sel_hi:[1,1,0]
	s_nop 0
	v_pk_fma_f32 v[146:147], v[128:129], v[146:147], s[84:85] op_sel_hi:[1,1,0]
	s_nop 0
	v_pk_fma_f32 v[146:147], v[128:129], v[146:147], s[64:65] op_sel_hi:[1,1,0]
	s_nop 0
	v_pk_mul_f32 v[128:129], v[128:129], v[146:147]
	s_nop 0
	v_pk_mul_f32 v[128:129], v[140:141], v[128:129]
	s_nop 0
	v_pk_mul_f32 v[140:141], v[126:127], v[128:129]
	v_pk_fma_f32 v[126:127], v[126:127], v[128:129], v[126:127] neg_lo:[1,0,0] neg_hi:[1,0,0]
	s_nop 0
	v_cndmask_b32_e64 v127, v127, v141, s[0:1]
	v_cndmask_b32_e32 v126, v126, v140, vcc
	v_pk_mul_f32 v[126:127], v[126:127], v[144:145]
	s_nop 0
	v_cvt_pk_bf16_f32 v110, v126, v127
	v_pk_mul_f32 v[126:127], v[18:19], v[152:153]
	s_nop 0
	v_pk_fma_f32 v[118:119], v[2:3], v[118:119], v[126:127]
	v_lshlrev_b32_e32 v126, 16, v107
	v_and_b32_e32 v127, 0xffff0000, v107
	v_pk_fma_f32 v[118:119], v[26:27], v[126:127], v[118:119]
	v_lshlrev_b32_e32 v126, 16, v103
	v_and_b32_e32 v127, 0xffff0000, v103
	v_pk_add_f32 v[118:119], v[78:79], v[118:119]
	v_pk_fma_f32 v[116:117], v[50:51], v[126:127], v[116:117]
	s_nop 0
	v_pk_add_f32 v[116:117], v[118:119], v[116:117]
	v_lshlrev_b32_e32 v118, 16, v111
	v_pk_add_f32 v[112:113], v[116:117], v[112:113]
	v_and_b32_e32 v119, 0xffff0000, v111
	v_fma_f32 v9, |v112|, s80, 1.0
	v_pk_mul_f32 v[116:117], v[112:113], v[112:113]
	v_rcp_f32_e32 v114, v9
	v_mul_f32_e32 v9, 0xbf38aa3b, v116
	v_exp_f32_e32 v116, v9
	v_fma_f32 v9, |v113|, s80, 1.0
	v_rcp_f32_e32 v115, v9
	v_mul_f32_e32 v9, 0xbf38aa3b, v117
	v_exp_f32_e32 v117, v9
	v_cmp_gt_f32_e32 vcc, 0, v112
	v_pk_fma_f32 v[124:125], v[114:115], s[68:69], v[124:125] op_sel_hi:[1,0,0]
	v_cmp_gt_f32_e64 s[0:1], 0, v113
	v_pk_fma_f32 v[124:125], v[114:115], v[124:125], s[44:45] op_sel_hi:[1,1,0]
	s_nop 0
	v_pk_fma_f32 v[124:125], v[114:115], v[124:125], s[84:85] op_sel_hi:[1,1,0]
	s_nop 0
	v_pk_fma_f32 v[124:125], v[114:115], v[124:125], s[64:65] op_sel_hi:[1,1,0]
	s_nop 0
	v_pk_mul_f32 v[114:115], v[114:115], v[124:125]
	s_nop 0
	v_pk_mul_f32 v[114:115], v[116:117], v[114:115]
	s_nop 0
	v_pk_mul_f32 v[116:117], v[112:113], v[114:115]
	v_pk_fma_f32 v[112:113], v[112:113], v[114:115], v[112:113] neg_lo:[1,0,0] neg_hi:[1,0,0]
	s_nop 0
	v_cndmask_b32_e64 v113, v113, v117, s[0:1]
	v_cndmask_b32_e32 v112, v112, v116, vcc
	v_pk_mul_f32 v[112:113], v[112:113], v[118:119]
	s_nop 0
	v_cvt_pk_bf16_f32 v111, v112, v113
	global_store_dwordx4 v[10:11], v[108:111], off offset:2560
	s_cbranch_scc1 .LBB0_701
